# grid barrier: L1 invalidate issued before polling for the release (overlaps the wait) in both leader and non-leader paths
# speedup vs baseline: 1.0099x; 1.0099x over previous
.LBB0_29:
	v_readlane_b32 s0, v253, 38
	v_readlane_b32 s1, v253, 39
	v_cvt_f32_u32_e32 v0, v3
	v_sub_u32_e32 v5, 0, v3
	v_rcp_iflag_f32_e32 v0, v0
	s_nop 1
	global_atomic_add v4, v1, v209, s[0:1] sc0
	v_mul_f32_e32 v0, 0x4f7ffffe, v0
	v_cvt_u32_f32_e32 v0, v0
	v_mul_lo_u32 v5, v5, v0
	v_mul_hi_u32 v5, v0, v5
	v_add_u32_e32 v0, v0, v5
	s_waitcnt vmcnt(0)
	v_mul_hi_u32 v0, v4, v0
	v_mul_lo_u32 v5, v0, v3
	v_sub_u32_e32 v5, v4, v5
	v_add_u32_e32 v6, 1, v0
	v_cmp_ge_u32_e32 vcc, v5, v3
	v_add_u32_e32 v4, 1, v4
	s_nop 0
	v_cndmask_b32_e32 v0, v0, v6, vcc
	v_sub_u32_e32 v6, v5, v3
	v_cndmask_b32_e32 v5, v5, v6, vcc
	v_add_u32_e32 v6, 1, v0
	v_cmp_ge_u32_e32 vcc, v5, v3
	s_nop 1
	v_cndmask_b32_e32 v0, v0, v6, vcc
	v_mul_lo_u32 v5, v3, v0
	v_add_u32_e32 v3, v5, v3
	v_cmp_ne_u32_e32 vcc, v4, v3
	s_and_saveexec_b64 s[0:1], vcc
	s_xor_b64 s[0:1], exec, s[0:1]
	s_cbranch_execz .LBB0_43
	buffer_inv sc1
	v_readlane_b32 s2, v253, 40
	v_readlane_b32 s3, v253, 41
	s_waitcnt lgkmcnt(0)
	s_nop 3
	global_load_dword v2, v1, s[2:3] sc1
	s_waitcnt vmcnt(0)
	v_cmp_eq_u32_e32 vcc, v2, v0
	s_and_saveexec_b64 s[2:3], vcc
	s_cbranch_execz .LBB0_42
	s_mov_b32 s16, 1
	s_mov_b64 s[6:7], 0
	s_branch .LBB0_33

.LBB0_42:
	s_or_b64 exec, exec, s[2:3]
	s_waitcnt vmcnt(0)
	s_waitcnt vmcnt(0)
.LBB0_43:
	s_andn2_saveexec_b64 s[0:1], s[0:1]
	s_cbranch_execz .LBB0_61
	s_mov_b64 s[0:1], exec
	buffer_wbl2 sc1
	s_waitcnt lgkmcnt(0)
	s_waitcnt vmcnt(0)
	buffer_inv sc1
	v_mbcnt_lo_u32_b32 v0, s0, 0
	v_mbcnt_hi_u32_b32 v0, s1, v0
	v_cmp_eq_u32_e32 vcc, 0, v0
	s_and_saveexec_b64 s[2:3], vcc
	s_cbranch_execz .LBB0_46
	s_bcnt1_i32_b64 s0, s[0:1]
	v_mov_b32_e32 v3, s0
	v_readlane_b32 s0, v253, 42
	v_readlane_b32 s1, v253, 43
	s_nop 4
	global_atomic_add v3, v1, v3, s[0:1] sc0

.LBB0_60:
	s_or_b64 exec, exec, s[0:1]
	v_readlane_b32 s0, v253, 40
	v_readlane_b32 s1, v253, 41
	s_waitcnt vmcnt(0)
	s_nop 0
	s_nop 2
	global_atomic_add v1, v209, s[0:1]
	s_waitcnt vmcnt(0)
